# first grid barrier also invalidates L1 at arrival instead of after release (on top of U-unit interleave and phase 8/18 offset)
# speedup vs baseline: 1.0230x; 1.0035x over previous
.LBB0_68:
	s_or_b64 exec, exec, s[8:9]
	s_lshr_b32 s0, s3, 16
	s_cmp_lg_u32 s0, 0
	s_cselect_b64 s[0:1], -1, 0
	s_cmp_lg_u64 s[0:1], 0
	s_addc_u32 s0, s5, 0
	s_waitcnt vmcnt(0)
	v_writelane_b32 v236, s0, 0
	s_and_b32 s0, s3, 0xffff
	s_cmp_lg_u32 s0, 0
	s_cselect_b64 s[0:1], -1, 0
	s_cmp_lg_u64 s[0:1], 0
	v_mov_b32_e32 v0, v205
	s_addc_u32 s0, s4, 0
	s_barrier
	v_writelane_b32 v236, s0, 1
	v_cmp_eq_u32_e32 vcc, 0, v0
	s_and_saveexec_b64 s[0:1], vcc
	s_cbranch_execz .LBB0_120
	buffer_inv sc1
	v_mov_b32_e32 v0, 0x12000
	s_waitcnt vmcnt(0) expcnt(0) lgkmcnt(0)
	ds_read_b32 v2, v0
	v_mov_b32_e32 v0, 0x12004
	ds_read_b32 v0, v0
	s_waitcnt lgkmcnt(1)
	v_cmp_ne_u32_e32 vcc, 0, v2
	s_cbranch_vccnz .LBB0_84
	v_readlane_b32 s3, v236, 0
	s_mul_i32 s3, s3, s92
	v_readlane_b32 s4, v236, 1
	s_mul_i32 s3, s3, s4
	s_add_u32 s4, s26, 0x1dc00200
	s_addc_u32 s5, s27, 0
	s_add_u32 s8, s26, 0x1dc00400
	s_addc_u32 s9, s27, 0
	s_add_u32 s10, s26, 0x1dc00500
	s_addc_u32 s11, s27, 0
	s_add_u32 s12, s26, 0x1dc00600
	s_addc_u32 s13, s27, 0
	s_add_u32 s14, s26, 0x1dc00700
	s_addc_u32 s15, s27, 0
	s_add_u32 s16, s26, 0x1dc00800
	s_addc_u32 s17, s27, 0
	s_add_u32 s18, s26, 0x1dc00900
	s_addc_u32 s19, s27, 0
	s_add_u32 s20, s26, 0x1dc00a00
	s_addc_u32 s21, s27, 0
	s_add_u32 s44, s26, 0x1dc00b00
	s_addc_u32 s45, s27, 0
	s_add_u32 s64, s26, 0x1dc00c00
	s_addc_u32 s65, s27, 0
	s_add_u32 s68, s26, 0x1dc00d00
	s_addc_u32 s69, s27, 0
	s_add_u32 s70, s26, 0x1dc00e00
	s_addc_u32 s71, s27, 0
	s_add_u32 s72, s26, 0x1dc00f00
	s_addc_u32 s73, s27, 0
	s_add_u32 s74, s26, 0x1dc01000
	s_addc_u32 s75, s27, 0
	s_add_u32 s76, s26, 0x1dc01100
	s_addc_u32 s77, s27, 0
	s_add_u32 s78, s26, 0x1dc01200
	s_addc_u32 s79, s27, 0
	s_add_u32 s80, s26, 0x1dc01300
	s_addc_u32 s81, s27, 0
	s_mov_b32 s88, 1
	v_mov_b32_e32 v16, 0
	s_branch .LBB0_72

.LBB0_99:
	s_or_b64 exec, exec, s[10:11]
	s_waitcnt vmcnt(0)
	s_nop 0
	s_waitcnt vmcnt(0)

.LBB0_117:
	s_or_b64 exec, exec, s[8:9]
	s_mov_b64 s[8:9], exec
	v_mbcnt_lo_u32_b32 v0, s8, 0
	v_mbcnt_hi_u32_b32 v0, s9, v0
	v_cmp_eq_u32_e32 vcc, 0, v0
	s_waitcnt vmcnt(0)
	s_nop 0
	s_and_saveexec_b64 s[10:11], vcc
	s_cbranch_execz .LBB0_119
	s_bcnt1_i32_b64 s3, s[8:9]
	v_mov_b32_e32 v0, 0x2000
	v_mov_b32_e32 v1, s3
	global_atomic_add v0, v1, s[4:5] offset:1024
